# P2a pool items rebalanced: GEMM-unit WGs take 12 of 16 items, partner WG takes the rest
# speedup vs baseline: 1.0007x; 1.0007x over previous
.LBB0_616:
	s_movk_i32 s98, 0x1000
	s_mov_b32 s99, 0
	s_cmp_lg_u32 s92, 0x100
	s_cbranch_scc1 .Lpool_e616
	s_movk_i32 s98, 3072

.LBB0_617:
	s_movk_i32 s98, 0x1000
	s_mov_b32 s99, 0
	s_cmp_lg_u32 s92, 0x100
	s_cbranch_scc1 .Lpool_e617
	s_mov_b32 s99, 1

.LBB0_619:
	s_or_b64 exec, exec, s[0:1]
	s_waitcnt vmcnt(0)
	v_lshlrev_b32_e32 v70, 16, v52
	v_and_b32_e32 v71, 0xffff0000, v52
	v_cvt_f32_ubyte0_e32 v52, v74
	v_lshlrev_b32_e32 v76, 16, v53
	v_and_b32_e32 v77, 0xffff0000, v53
	v_div_scale_f32 v53, s[0:1], v52, v52, 1.0
	v_rcp_f32_e32 v74, v53
	v_lshlrev_b32_e32 v88, 16, v58
	v_and_b32_e32 v89, 0xffff0000, v58
	v_lshlrev_b32_e32 v80, 16, v60
	v_fma_f32 v58, -v53, v74, 1.0
	v_fmac_f32_e32 v74, v58, v74
	v_div_scale_f32 v58, vcc, 1.0, v52, 1.0
	v_and_b32_e32 v81, 0xffff0000, v60
	v_lshlrev_b32_e32 v82, 16, v61
	v_and_b32_e32 v83, 0xffff0000, v61
	v_lshlrev_b32_e32 v84, 16, v62
	v_and_b32_e32 v85, 0xffff0000, v62
	v_lshlrev_b32_e32 v60, 16, v63
	v_and_b32_e32 v61, 0xffff0000, v63
	v_lshlrev_b32_e32 v62, 16, v56
	v_and_b32_e32 v63, 0xffff0000, v56
	v_lshlrev_b32_e32 v86, 16, v57
	v_and_b32_e32 v87, 0xffff0000, v57
	v_lshlrev_b32_e32 v56, 16, v59
	v_and_b32_e32 v57, 0xffff0000, v59
	v_mul_f32_e32 v59, v58, v74
	v_fma_f32 v75, -v53, v59, v58
	v_fmac_f32_e32 v59, v75, v74
	v_fma_f32 v53, -v53, v59, v58
	v_div_fmas_f32 v53, v53, v74, v59
	v_lshlrev_b32_e32 v58, 16, v0
	v_and_b32_e32 v59, 0xffff0000, v0
	v_lshlrev_b32_e32 v74, 16, v4
	v_and_b32_e32 v75, 0xffff0000, v4
	v_pk_add_f32 v[100:101], v[58:59], 0 op_sel_hi:[1,0]
	v_lshlrev_b32_e32 v90, 16, v12
	v_and_b32_e32 v91, 0xffff0000, v12
	v_pk_add_f32 v[74:75], v[100:101], v[74:75]
	v_lshlrev_b32_e32 v92, 16, v8
	v_and_b32_e32 v93, 0xffff0000, v8
	v_pk_add_f32 v[74:75], v[74:75], v[90:91]
	v_lshlrev_b32_e32 v94, 16, v16
	v_and_b32_e32 v95, 0xffff0000, v16
	v_pk_add_f32 v[74:75], v[74:75], v[92:93]
	v_lshlrev_b32_e32 v96, 16, v20
	v_and_b32_e32 v97, 0xffff0000, v20
	v_pk_add_f32 v[74:75], v[74:75], v[94:95]
	v_lshlrev_b32_e32 v98, 16, v24
	v_and_b32_e32 v99, 0xffff0000, v24
	v_pk_add_f32 v[74:75], v[74:75], v[96:97]
	v_div_fixup_f32 v52, v53, v52, 1.0
	v_pk_add_f32 v[74:75], v[74:75], v[98:99]
	v_lshlrev_b32_e32 v4, 16, v5
	v_pk_add_f32 v[70:71], v[74:75], v[70:71]
	v_and_b32_e32 v5, 0xffff0000, v5
	v_pk_add_f32 v[70:71], v[70:71], v[80:81]
	v_lshlrev_b32_e32 v12, 16, v13
	v_pk_add_f32 v[62:63], v[70:71], v[62:63]
	v_lshlrev_b32_e32 v70, 16, v32
	v_and_b32_e32 v71, 0xffff0000, v32
	v_pk_add_f32 v[62:63], v[62:63], v[70:71]
	v_lshlrev_b32_e32 v70, 16, v28
	v_and_b32_e32 v71, 0xffff0000, v28
	v_pk_add_f32 v[62:63], v[62:63], v[70:71]
	v_lshlrev_b32_e32 v70, 16, v40
	v_and_b32_e32 v71, 0xffff0000, v40
	v_pk_add_f32 v[62:63], v[62:63], v[70:71]
	v_lshlrev_b32_e32 v70, 16, v36
	v_and_b32_e32 v71, 0xffff0000, v36
	v_pk_add_f32 v[62:63], v[62:63], v[70:71]
	v_lshlrev_b32_e32 v70, 16, v48
	v_and_b32_e32 v71, 0xffff0000, v48
	v_pk_add_f32 v[62:63], v[62:63], v[70:71]
	v_lshlrev_b32_e32 v70, 16, v44
	v_and_b32_e32 v71, 0xffff0000, v44
	v_pk_add_f32 v[62:63], v[62:63], v[70:71]
	v_and_b32_e32 v13, 0xffff0000, v13
	v_pk_fma_f32 v[58:59], v[52:53], v[62:63], v[58:59] op_sel_hi:[0,1,1] neg_lo:[0,0,1] neg_hi:[0,0,1]
	v_cvt_pk_bf16_f32 v0, v58, v59
	v_lshlrev_b32_e32 v58, 16, v1
	v_and_b32_e32 v59, 0xffff0000, v1
	v_pk_add_f32 v[62:63], v[58:59], 0 op_sel_hi:[1,0]
	v_lshlrev_b32_e32 v8, 16, v9
	v_pk_add_f32 v[4:5], v[62:63], v[4:5]
	v_and_b32_e32 v9, 0xffff0000, v9
	v_pk_add_f32 v[4:5], v[4:5], v[12:13]
	v_lshlrev_b32_e32 v16, 16, v17
	v_and_b32_e32 v17, 0xffff0000, v17
	v_pk_add_f32 v[4:5], v[4:5], v[8:9]
	v_lshlrev_b32_e32 v20, 16, v21
	v_and_b32_e32 v21, 0xffff0000, v21
	v_pk_add_f32 v[4:5], v[4:5], v[16:17]
	v_lshlrev_b32_e32 v24, 16, v25
	v_and_b32_e32 v25, 0xffff0000, v25
	v_pk_add_f32 v[4:5], v[4:5], v[20:21]
	v_lshlrev_b32_e32 v8, 16, v33
	v_pk_add_f32 v[4:5], v[4:5], v[24:25]
	v_and_b32_e32 v9, 0xffff0000, v33
	v_pk_add_f32 v[4:5], v[4:5], v[76:77]
	v_lshlrev_b32_e32 v12, 16, v14
	v_pk_add_f32 v[4:5], v[4:5], v[82:83]
	v_and_b32_e32 v13, 0xffff0000, v14
	v_pk_add_f32 v[4:5], v[4:5], v[86:87]
	v_lshlrev_b32_e32 v16, 16, v10
	v_pk_add_f32 v[4:5], v[4:5], v[8:9]
	v_lshlrev_b32_e32 v8, 16, v29
	v_and_b32_e32 v9, 0xffff0000, v29
	v_pk_add_f32 v[4:5], v[4:5], v[8:9]
	v_lshlrev_b32_e32 v8, 16, v41
	v_and_b32_e32 v9, 0xffff0000, v41
	v_pk_add_f32 v[4:5], v[4:5], v[8:9]
	v_lshlrev_b32_e32 v8, 16, v37
	v_and_b32_e32 v9, 0xffff0000, v37
	v_pk_add_f32 v[4:5], v[4:5], v[8:9]
	v_lshlrev_b32_e32 v8, 16, v49
	v_and_b32_e32 v9, 0xffff0000, v49
	v_pk_add_f32 v[4:5], v[4:5], v[8:9]
	v_lshlrev_b32_e32 v8, 16, v45
	v_and_b32_e32 v9, 0xffff0000, v45
	v_pk_add_f32 v[4:5], v[4:5], v[8:9]
	v_lshlrev_b32_e32 v8, 16, v6
	v_pk_fma_f32 v[4:5], v[52:53], v[4:5], v[58:59] op_sel_hi:[0,1,1] neg_lo:[0,0,1] neg_hi:[0,0,1]
	v_cvt_pk_bf16_f32 v1, v4, v5
	v_lshlrev_b32_e32 v4, 16, v2
	v_and_b32_e32 v5, 0xffff0000, v2
	v_and_b32_e32 v9, 0xffff0000, v6
	v_pk_add_f32 v[32:33], v[4:5], 0 op_sel_hi:[1,0]
	v_and_b32_e32 v17, 0xffff0000, v10
	v_pk_add_f32 v[8:9], v[32:33], v[8:9]
	v_lshlrev_b32_e32 v20, 16, v18
	v_pk_add_f32 v[8:9], v[8:9], v[12:13]
	v_and_b32_e32 v21, 0xffff0000, v18
	v_pk_add_f32 v[8:9], v[8:9], v[16:17]
	v_lshlrev_b32_e32 v24, 16, v22
	v_and_b32_e32 v25, 0xffff0000, v22
	v_pk_add_f32 v[8:9], v[8:9], v[20:21]
	v_lshlrev_b32_e32 v28, 16, v26
	v_and_b32_e32 v29, 0xffff0000, v26
	v_pk_add_f32 v[8:9], v[8:9], v[24:25]
	v_lshlrev_b32_e32 v78, 16, v54
	v_and_b32_e32 v79, 0xffff0000, v54
	v_pk_add_f32 v[8:9], v[8:9], v[28:29]
	v_lshlrev_b32_e32 v12, 16, v34
	v_pk_add_f32 v[8:9], v[8:9], v[78:79]
	v_and_b32_e32 v13, 0xffff0000, v34
	v_pk_add_f32 v[8:9], v[8:9], v[84:85]
	v_lshlrev_b32_e32 v6, 16, v7
	v_pk_add_f32 v[8:9], v[8:9], v[88:89]
	v_and_b32_e32 v7, 0xffff0000, v7
	v_pk_add_f32 v[8:9], v[8:9], v[12:13]
	v_lshlrev_b32_e32 v12, 16, v30
	v_and_b32_e32 v13, 0xffff0000, v30
	v_pk_add_f32 v[8:9], v[8:9], v[12:13]
	v_lshlrev_b32_e32 v12, 16, v42
	v_and_b32_e32 v13, 0xffff0000, v42
	v_pk_add_f32 v[8:9], v[8:9], v[12:13]
	v_lshlrev_b32_e32 v12, 16, v38
	v_and_b32_e32 v13, 0xffff0000, v38
	v_pk_add_f32 v[8:9], v[8:9], v[12:13]
	v_lshlrev_b32_e32 v12, 16, v50
	v_and_b32_e32 v13, 0xffff0000, v50
	v_pk_add_f32 v[8:9], v[8:9], v[12:13]
	v_lshlrev_b32_e32 v12, 16, v46
	v_and_b32_e32 v13, 0xffff0000, v46
	v_pk_add_f32 v[8:9], v[8:9], v[12:13]
	v_lshlrev_b32_e32 v12, 16, v19
	v_pk_fma_f32 v[4:5], v[52:53], v[8:9], v[4:5] op_sel_hi:[0,1,1] neg_lo:[0,0,1] neg_hi:[0,0,1]
	v_cvt_pk_bf16_f32 v2, v4, v5
	v_lshlrev_b32_e32 v4, 16, v3
	v_and_b32_e32 v5, 0xffff0000, v3
	v_and_b32_e32 v13, 0xffff0000, v19
	v_pk_add_f32 v[18:19], v[4:5], 0 op_sel_hi:[1,0]
	v_lshlrev_b32_e32 v8, 16, v15
	v_and_b32_e32 v9, 0xffff0000, v15
	v_pk_add_f32 v[6:7], v[18:19], v[6:7]
	v_lshlrev_b32_e32 v10, 16, v11
	v_and_b32_e32 v11, 0xffff0000, v11
	v_pk_add_f32 v[6:7], v[6:7], v[8:9]
	v_lshlrev_b32_e32 v14, 16, v23
	v_pk_add_f32 v[6:7], v[6:7], v[10:11]
	v_and_b32_e32 v15, 0xffff0000, v23
	v_pk_add_f32 v[6:7], v[6:7], v[12:13]
	v_lshlrev_b32_e32 v16, 16, v27
	v_and_b32_e32 v17, 0xffff0000, v27
	v_pk_add_f32 v[6:7], v[6:7], v[14:15]
	v_lshlrev_b32_e32 v54, 16, v55
	v_and_b32_e32 v55, 0xffff0000, v55
	v_pk_add_f32 v[6:7], v[6:7], v[16:17]
	v_lshlrev_b32_e32 v8, 16, v35
	v_pk_add_f32 v[6:7], v[6:7], v[54:55]
	v_and_b32_e32 v9, 0xffff0000, v35
	v_pk_add_f32 v[6:7], v[6:7], v[60:61]
	v_lshlrev_b64 v[68:69], 9, v[68:69]
	v_pk_add_f32 v[6:7], v[6:7], v[56:57]
	s_add_i32 s3, s3, s92
	v_pk_add_f32 v[6:7], v[6:7], v[8:9]
	v_lshlrev_b32_e32 v8, 16, v31
	v_and_b32_e32 v9, 0xffff0000, v31
	v_pk_add_f32 v[6:7], v[6:7], v[8:9]
	v_lshlrev_b32_e32 v8, 16, v43
	v_and_b32_e32 v9, 0xffff0000, v43
	v_pk_add_f32 v[6:7], v[6:7], v[8:9]
	v_lshlrev_b32_e32 v8, 16, v39
	v_and_b32_e32 v9, 0xffff0000, v39
	v_pk_add_f32 v[6:7], v[6:7], v[8:9]
	v_lshlrev_b32_e32 v8, 16, v51
	v_and_b32_e32 v9, 0xffff0000, v51
	v_pk_add_f32 v[6:7], v[6:7], v[8:9]
	v_lshlrev_b32_e32 v8, 16, v47
	v_and_b32_e32 v9, 0xffff0000, v47
	v_pk_add_f32 v[6:7], v[6:7], v[8:9]
	s_cmp_ge_i32 s3, s98
	v_pk_fma_f32 v[4:5], v[52:53], v[6:7], v[4:5] op_sel_hi:[0,1,1] neg_lo:[0,0,1] neg_hi:[0,0,1]
	v_cvt_pk_bf16_f32 v3, v4, v5
	v_lshl_add_u64 v[4:5], v[68:69], 1, v[66:67]
	v_add_u32_e32 v73, s2, v73
	global_store_dwordx4 v[4:5], v[0:3], off
	s_cbranch_scc1 .LBB0_650

.LBB0_650:
	s_cmp_eq_u32 s99, 1
	s_cbranch_scc0 .Lpool_done
	s_mov_b32 s99, 0
	s_xor_b32 s3, s62, 1
	s_add_i32 s3, s3, 3072
	v_lshl_add_u32 v73, s3, 9, v178
	s_movk_i32 s98, 0x1000
	s_branch .LBB0_620

	.amdhsa_kernel _Z18nsa_pool_block_fwd6Params
		.amdhsa_group_segment_fixed_size 0
		.amdhsa_private_segment_fixed_size 0
		.amdhsa_kernarg_size 624
		.amdhsa_user_sgpr_count 2
		.amdhsa_user_sgpr_dispatch_ptr 0
		.amdhsa_user_sgpr_queue_ptr 0
		.amdhsa_user_sgpr_kernarg_segment_ptr 1
		.amdhsa_user_sgpr_dispatch_id 0
		.amdhsa_user_sgpr_kernarg_preload_length 0
		.amdhsa_user_sgpr_kernarg_preload_offset 0
		.amdhsa_user_sgpr_private_segment_size 0
		.amdhsa_uses_dynamic_stack 0
		.amdhsa_enable_private_segment 0
		.amdhsa_system_sgpr_workgroup_id_x 1
		.amdhsa_system_sgpr_workgroup_id_y 0
		.amdhsa_system_sgpr_workgroup_id_z 0
		.amdhsa_system_sgpr_workgroup_info 0
		.amdhsa_system_vgpr_workitem_id 2
		.amdhsa_next_free_vgpr 254
		.amdhsa_next_free_sgpr 100
		.amdhsa_accum_offset 256
		.amdhsa_reserve_vcc 1
		.amdhsa_float_round_mode_32 0
		.amdhsa_float_round_mode_16_64 0
		.amdhsa_float_denorm_mode_32 3
		.amdhsa_float_denorm_mode_16_64 3
		.amdhsa_dx10_clamp 1
		.amdhsa_ieee_mode 1
		.amdhsa_fp16_overflow 0
		.amdhsa_tg_split 0
		.amdhsa_exception_fp_ieee_invalid_op 0
		.amdhsa_exception_fp_denorm_src 0
		.amdhsa_exception_fp_ieee_div_zero 0
		.amdhsa_exception_fp_ieee_overflow 0
		.amdhsa_exception_fp_ieee_underflow 0
		.amdhsa_exception_fp_ieee_inexact 0
		.amdhsa_exception_int_div_zero 0
	.end_amdhsa_kernel

amdhsa.kernels:
  - .agpr_count:     0
    .args:
      - .offset:         0
        .size:           368
        .value_kind:     by_value
      - .offset:         368
        .size:           4
        .value_kind:     hidden_block_count_x
      - .offset:         372
        .size:           4
        .value_kind:     hidden_block_count_y
      - .offset:         376
        .size:           4
        .value_kind:     hidden_block_count_z
      - .offset:         380
        .size:           2
        .value_kind:     hidden_group_size_x
      - .offset:         382
        .size:           2
        .value_kind:     hidden_group_size_y
      - .offset:         384
        .size:           2
        .value_kind:     hidden_group_size_z
      - .offset:         386
        .size:           2
        .value_kind:     hidden_remainder_x
      - .offset:         388
        .size:           2
        .value_kind:     hidden_remainder_y
      - .offset:         390
        .size:           2
        .value_kind:     hidden_remainder_z
      - .offset:         408
        .size:           8
        .value_kind:     hidden_global_offset_x
      - .offset:         416
        .size:           8
        .value_kind:     hidden_global_offset_y
      - .offset:         424
        .size:           8
        .value_kind:     hidden_global_offset_z
      - .offset:         432
        .size:           2
        .value_kind:     hidden_grid_dims
      - .offset:         456
        .size:           8
        .value_kind:     hidden_multigrid_sync_arg
      - .offset:         488
        .size:           4
        .value_kind:     hidden_dynamic_lds_size
    .group_segment_fixed_size: 0
    .kernarg_segment_align: 8
    .kernarg_segment_size: 624
    .language:       OpenCL C
    .language_version:
      - 2
      - 0
    .max_flat_workgroup_size: 512
    .name:           _Z18nsa_pool_block_fwd6Params
    .private_segment_fixed_size: 0
    .sgpr_count:     106
    .sgpr_spill_count: 123
    .symbol:         _Z18nsa_pool_block_fwd6Params.kd
    .uniform_work_group_size: 1
    .uses_dynamic_stack: false
    .vgpr_count:     254
    .vgpr_spill_count: 0
    .wavefront_size: 64
